# attention MoBA/MLA loops: priority (kh=0) waves issue the next tile's global loads before the step barrier (in their barrier slack) instead of after it
# baseline (speedup 1.0000x reference)
; template <int DQ, int TYPE>
; __device__ __forceinline__ void attn_item(PP p, int layer, int b, int h, int qt, char* lds, const int tid_, unsigned* next_ctr, volatile XLAS unsigned* slot) {
;     ...
;     A_LSTORE(A, 0); __syncthreads();
;     if (kh == 0) __builtin_amdgcn_s_setprio(2);
.LBB0_635:
	v_lshl_add_u32 v2, v185, 1, 16
	v_mul_lo_u32 v158, v166, s84
	v_add_u32_e32 v3, v2, v158
	v_mul_lo_u32 v159, v168, s84
	s_waitcnt vmcnt(11)
	ds_write_b128 v3, v[82:85]
	v_add_u32_e32 v3, v2, v159
	v_mul_u32_u24_e32 v4, 15, v185
	v_lshlrev_b32_e32 v160, 1, v170
	s_waitcnt vmcnt(10)
	ds_write_b128 v3, v[86:89]
	s_waitcnt vmcnt(9)
	v_and_b32_e32 v3, 0xffff, v106
	v_add3_u32 v2, v2, v4, v160
	v_lshrrev_b32_e32 v4, 16, v106
	s_waitcnt vmcnt(8)
	v_lshl_or_b32 v3, v118, 16, v3
	v_and_or_b32 v4, v118, s91, v4
	v_add_u32_e32 v2, 0x4400, v2
	ds_write_b32 v2, v3
	ds_write_b32 v2, v4 offset:2448
	v_and_b32_e32 v3, 0xffff, v107
	v_lshrrev_b32_e32 v4, 16, v107
	s_lshl_b32 s56, s96, 12
	s_lshl_b32 s55, s97, 7
	v_lshl_or_b32 v3, v119, 16, v3
	v_and_or_b32 v4, v119, s91, v4
	ds_write_b32 v2, v3 offset:4896
	ds_write_b32 v2, v4 offset:7344
	v_and_b32_e32 v3, 0xffff, v108
	v_lshrrev_b32_e32 v4, 16, v108
	s_cmpk_lt_u32 s88, 0x100
	v_lshl_or_b32 v3, v120, 16, v3
	v_and_or_b32 v4, v120, s91, v4
	s_cselect_b64 s[52:53], -1, 0
	s_cmpk_gt_u32 s88, 0xff
	ds_write_b32 v2, v3 offset:9792
	ds_write_b32 v2, v4 offset:12240
	v_and_b32_e32 v3, 0xffff, v109
	v_lshrrev_b32_e32 v4, 16, v109
	s_cselect_b64 s[8:9], -1, 0
	v_lshl_or_b32 v3, v121, 16, v3
	v_and_or_b32 v4, v121, s91, v4
	s_and_b64 vcc, exec, s[8:9]
	ds_write_b32 v2, v3 offset:14688
	ds_write_b32 v2, v4 offset:17136
	s_waitcnt lgkmcnt(0)
	s_barrier
	s_mov_b32 s32, 0
	s_cbranch_vccnz .LBB0_637
	s_setprio 2
	s_mov_b32 s32, 1

; template <int DQ, int TYPE>
; __device__ __forceinline__ void attn_item(PP p, int layer, int b, int h, int qt, char* lds, const int tid_, unsigned* next_ctr, volatile XLAS unsigned* slot) {
;     ...
;     for (int j = j_lo; j <= j_hi; ++j) {
;         const int buf = (j - j_lo) & 1;
;         if (j < j_hi) A_GLOAD(A, j + 1);
.LBB0_638:
	v_mov_b32_e32 v176, v165
	s_cmp_le_u32 s61, s57
	s_cselect_b64 s[12:13], -1, 0
	s_cmp_gt_u32 s61, s57
	s_cbranch_scc1 .LBB0_640
	s_cmp_lg_u32 s32, 0
	s_cbranch_scc1 .LBB0_640

; template <int DQ, int TYPE>
; __device__ __forceinline__ void attn_item(PP p, int layer, int b, int h, int qt, char* lds, const int tid_, unsigned* next_ctr, volatile XLAS unsigned* slot) {
;     ...
;     for (int j = j_lo; j <= j_hi; ++j) {
;         const int buf = (j - j_lo) & 1;
;         if (j < j_hi) A_GLOAD(A, j + 1);
;     ...
;         if (j < j_hi) A_LSTORE(A, buf ^ 1);
;         __syncthreads();
;     }
;     ...
;     __builtin_amdgcn_s_setprio(0);
;     unsigned nxt_item = 0; if (tid_ == 0) nxt_item = atomicAdd(next_ctr, 1u);
.LBB0_648:
	s_add_i32 s61, s61, 1
	s_add_i32 s62, s62, 64
	s_waitcnt lgkmcnt(0)
	s_cmp_eq_u32 s32, 0
	s_cbranch_scc1 .Lmoba_noearly
	s_cmp_eq_u32 s60, s61
	s_cbranch_scc1 .Lmoba_noearly
	s_cmp_gt_u32 s61, s57
	s_cbranch_scc1 .Lmoba_noearly
	global_load_dwordx4 v[82:85], v[232:233], off
	global_load_dwordx4 v[86:89], v[234:235], off
	global_load_dwordx4 v[106:109], v[236:237], off
	global_load_dwordx4 v[118:121], v[236:237], off offset:1024
	v_lshl_add_u64 v[232:233], s[98:99], 0, v[232:233]
	v_lshl_add_u64 v[234:235], s[98:99], 0, v[234:235]
	v_lshl_add_u64 v[236:237], s[98:99], 0, v[236:237]
.Lmoba_noearly:
	s_cmp_eq_u32 s60, s61
	s_barrier
	s_cbranch_scc0 .LBB0_638
	s_setprio 0
	v_mov_b32_e32 v74, 0
	v_cmp_eq_u32_e64 s[50:51], 0, v181
	s_and_saveexec_b64 s[12:13], s[50:51]
	s_cbranch_execz .LBB0_653
	s_mov_b64 s[16:17], exec
	v_mbcnt_lo_u32_b32 v66, s16, 0
	v_mbcnt_hi_u32_b32 v66, s17, v66
	v_cmp_eq_u32_e32 vcc, 0, v66
	s_and_saveexec_b64 s[14:15], vcc
	s_cbranch_execz .LBB0_652
	s_bcnt1_i32_b64 s16, s[16:17]
	s_lshl_b32 s17, s47, 2
	v_mov_b32_e32 v67, s17
	v_mov_b32_e32 v68, s16
	global_atomic_add v250, v67, v68, s[6:7] sc0

; template <int DQ, int TYPE>
; __device__ __forceinline__ void attn_item(PP p, int layer, int b, int h, int qt, char* lds, const int tid_, unsigned* next_ctr, volatile XLAS unsigned* slot) {
;     ...
;     const bf16_t *Qp, *Kp, *Vp, *Kpe = nullptr; int ldq, ldk, ldv; bf16_t* Op; float scale;
;     if (TYPE == 0) {
;         Qp = (const bf16_t*)(p->ws + OFF_QB) + tok0 * 768 + h * 192; ldq = 768;
;         Kp = (const bf16_t*)(p->ws + OFF_KVB) + tok0 * 1024 + h * 256; ldk = 1024;
;         Vp = Kp + 128; ldv = 1024;
;         Kpe = (const bf16_t*)(p->ws + OFF_KPE) + tok0 * 64;
;         Op = (bf16_t*)(p->ws + OFF_OB) + tok0 * D + h * 128; scale = 0.07216878364870322f;
;     } else if (TYPE == 1) {
;         Qp = (const bf16_t*)(p->ws + OFF_MQ) + tok0 * 512 + h * 128; ldq = 512;
;         Kp = (const bf16_t*)(p->ws + OFF_MK) + tok0 * 512 + h * 128; ldk = 512;
;         Vp = (const bf16_t*)(p->ws + OFF_MV) + tok0 * 512 + h * 128; ldv = 512;
;         Op = (bf16_t*)(p->ws + OFF_OB) + tok0 * D + 512 + h * 128; scale = 0.08838834764831845f;
;     } else {
;         Qp = (const bf16_t*)(p->ws + OFF_SQ) + tok0 * 1024 + h * 128; ldq = 1024;
;         Kp = (const bf16_t*)(p->ws + OFF_SK) + tok0 * 256 + (h >> 2) * 128; ldk = 256;
;         Vp = (const bf16_t*)(p->ws + OFF_SV) + tok0 * 256 + (h >> 2) * 128; ldv = 256;
;         Op = (bf16_t*)(p->ws + OFF_OB) + tok0 * D + 1024 + h * 128; scale = 0.08838834764831845f;
;     }
;     const float c = scale * LOG2E;
;     const int j_hi = 2 * qt + 1, j_lo = (TYPE == 2) ? (qt > 0 ? 2 * qt - 2 : 0) : 0;
;     const int own = qt >> 1;
;     const int qpos = 128 * qt + 32 * qg + r;
;     u32x4 kregA[DQ == 192 ? 3 : 2], vregA[2];
;     const int dg = t & 15, kp = t >> 4;
;     ...
;     A_GLOAD(A, j_lo);
;     bf16x8 qf[NKS];
;     {
;         const bf16_t* qrow = Qp + (size_t)qpos * ldq + 8 * hh;
; #pragma unroll
;         for (int ks = 0; ks < NKS; ++ks) qf[ks] = *(const bf16x8*)(qrow + 16 * ks);
;         if (TYPE == 0) {
;             const float* r64 = (const float*)(p->ws + OFF_R64) + (size_t)qpos * 64;
; #pragma unroll
;             for (int kk = 0; kk < 2; ++kk) {
;                 bf16x8 x1 = qf[8 + kk], x2 = qf[10 + kk], o1, o2;
; #pragma unroll
;                 for (int j = 0; j < 8; ++j) {
;                     const int f = 16 * kk + 8 * hh + j;
;                     const float cs = r64[2 * f], sn = r64[2 * f + 1];
.LBB0_658:
	s_and_b64 vcc, exec, s[8:9]
	s_cbranch_vccz .LBB0_385
	s_lshl_b32 s8, s47, 10
	v_readfirstlane_b32 s14, v181
	s_and_b32 s55, s8, 0x1000
	s_and_b32 s54, s48, 3
	s_bfe_u32 s48, s14, 0x20006
	s_lshl_b32 s8, s55, 11
	s_add_u32 s8, s36, s8
	s_addc_u32 s9, s37, 0
	s_lshl_b32 s13, s54, 9
	s_add_u32 s8, s8, s13
	s_addc_u32 s9, s9, 0
	s_lshl_b32 s15, s80, 7
	s_lshl_b32 s16, s48, 5
	s_mul_i32 s12, s55, 0x600
	s_lshl_b32 s13, s55, 7
	s_or_b32 s15, s16, s15
	s_add_u32 s16, s40, s12
	s_addc_u32 s17, s41, 0
	s_add_u32 s12, s44, s13
	s_addc_u32 s13, s45, 0
	s_mul_i32 s50, s54, 0x180
	s_add_u32 s16, s16, s50
	s_addc_u32 s17, s17, 0
	v_or_b32_e32 v172, s15, v154
	v_mov_b64_e32 v[2:3], s[16:17]
	s_movk_i32 s16, 0x600
	v_mov_b32_e32 v173, v1
	v_mad_u64_u32 v[2:3], s[16:17], v172, s16, v[2:3]
	v_mov_b32_e32 v147, v1
	v_lshlrev_b64 v[4:5], 8, v[172:173]
	v_lshl_add_u64 v[22:23], v[2:3], 0, v[146:147]
	v_lshlrev_b32_e32 v2, 6, v155
	v_mov_b32_e32 v3, v1
	v_lshl_add_u64 v[4:5], s[2:3], 0, v[4:5]
	global_load_dwordx4 v[10:13], v[22:23], off offset:256
	global_load_dwordx4 v[14:17], v[22:23], off offset:320
	v_lshl_add_u64 v[20:21], v[4:5], 0, v[2:3]
	global_load_dwordx2 v[24:25], v[20:21], off
	v_lshlrev_b32_e32 v18, 1, v185
	v_mov_b32_e32 v19, v1
	v_ashrrev_i32_e32 v174, 3, v181
	v_lshlrev_b64 v[2:3], 11, v[166:167]
	v_ashrrev_i32_e32 v169, 31, v168
	v_ashrrev_i32_e32 v175, 31, v174
	v_lshl_add_u64 v[176:177], s[8:9], 0, v[18:19]
	v_and_b32_e32 v0, 56, v156
	v_ashrrev_i32_e32 v171, 31, v170
	v_lshlrev_b64 v[4:5], 11, v[168:169]
	v_lshlrev_b64 v[8:9], 7, v[174:175]
	v_lshl_add_u64 v[2:3], v[176:177], 0, v[2:3]
	v_lshlrev_b32_e32 v0, 1, v0
	v_lshlrev_b64 v[6:7], 11, v[170:171]
	v_lshl_add_u64 v[4:5], v[176:177], 0, v[4:5]
	global_load_dwordx4 v[86:89], v[2:3], off
	global_load_dwordx4 v[90:93], v[4:5], off
	v_lshl_add_u64 v[2:3], s[12:13], 0, v[8:9]
	v_lshl_add_u64 v[26:27], v[176:177], 0, v[6:7]
	v_lshl_add_u64 v[2:3], v[2:3], 0, v[0:1]
	global_load_dwordx4 v[114:117], v[26:27], off offset:256
	global_load_dwordx4 v[118:121], v[2:3], off
	s_nop 0
	global_load_dwordx4 v[2:5], v[22:23], off offset:288
	global_load_dwordx4 v[82:85], v[22:23], off offset:224
	global_load_dwordx4 v[6:9], v[22:23], off offset:352
	global_load_dwordx4 v[122:125], v[26:27], off offset:2304
	global_load_dwordx4 v[94:97], v[22:23], off
	global_load_dwordx4 v[98:101], v[22:23], off offset:32
	global_load_dwordx4 v[102:105], v[22:23], off offset:64
	global_load_dwordx4 v[106:109], v[22:23], off offset:96
	global_load_dwordx4 v[110:113], v[22:23], off offset:128
	global_load_dwordx4 v[126:129], v[22:23], off offset:160
	global_load_dwordx4 v[130:133], v[22:23], off offset:192
	s_movk_i32 s8, 0x190
	v_mul_lo_u32 v189, v166, s8
	v_mul_lo_u32 v193, v168, s8
	s_movk_i32 s8, 0xc8
	v_add_u32_e32 v18, 16, v18
	s_cmpk_lt_u32 s14, 0x100
	s_cselect_b64 s[52:53], -1, 0
	s_cmpk_gt_u32 s14, 0xff
	s_movk_i32 s51, 0x190
	v_add_u32_e32 v42, v18, v189
	s_waitcnt vmcnt(17)
	v_lshlrev_b32_e32 v23, 16, v10
	s_waitcnt vmcnt(16)
	v_lshlrev_b32_e32 v22, 16, v14
	s_waitcnt vmcnt(15)
	v_pk_mul_f32 v[26:27], v[24:25], v[22:23] op_sel:[0,1] op_sel_hi:[1,0]
	v_pk_mul_f32 v[22:23], v[24:25], v[22:23]
	v_sub_f32_e32 v19, v26, v27
	v_add_f32_e32 v23, v23, v22
	v_cvt_pk_bf16_f32 v22, v19, v1
	v_cvt_pk_bf16_f32 v19, v23, v1
	global_load_dwordx2 v[24:25], v[20:21], off offset:8
	v_and_b32_e32 v27, 0xffff0000, v10
	v_and_b32_e32 v26, 0xffff0000, v14
	s_waitcnt vmcnt(13)
	v_and_b32_e32 v44, 0xffff, v116
	v_lshrrev_b32_e32 v45, 16, v116
	v_and_b32_e32 v46, 0xffff, v117
	v_lshrrev_b32_e32 v47, 16, v117
	s_waitcnt vmcnt(8)
	v_lshl_or_b32 v44, v124, 16, v44
	v_and_or_b32 v45, v124, s91, v45
	v_lshl_or_b32 v46, v125, 16, v46
	v_and_or_b32 v47, v125, s91, v47
	s_waitcnt vmcnt(0)
	v_pk_mul_f32 v[28:29], v[24:25], v[26:27] op_sel:[0,1] op_sel_hi:[1,0]
	v_pk_mul_f32 v[24:25], v[24:25], v[26:27]
	v_sub_f32_e32 v10, v28, v29
	v_add_f32_e32 v14, v24, v25
	v_cvt_pk_bf16_f32 v23, v10, v1
	v_cvt_pk_bf16_f32 v10, v14, v1
	global_load_dwordx2 v[24:25], v[20:21], off offset:16
	v_lshlrev_b32_e32 v27, 16, v11
	v_lshlrev_b32_e32 v26, 16, v15
	s_waitcnt vmcnt(0)
	v_pk_mul_f32 v[28:29], v[24:25], v[26:27] op_sel:[0,1] op_sel_hi:[1,0]
	v_pk_mul_f32 v[24:25], v[24:25], v[26:27]
	v_sub_f32_e32 v14, v28, v29
	v_add_f32_e32 v25, v24, v25
	v_cvt_pk_bf16_f32 v24, v14, v1
	v_cvt_pk_bf16_f32 v14, v25, v1
	global_load_dwordx2 v[26:27], v[20:21], off offset:24
	v_and_b32_e32 v29, 0xffff0000, v11
	v_and_b32_e32 v28, 0xffff0000, v15
	s_waitcnt vmcnt(0)
	v_pk_mul_f32 v[30:31], v[26:27], v[28:29] op_sel:[0,1] op_sel_hi:[1,0]
	v_pk_mul_f32 v[26:27], v[26:27], v[28:29]
	v_sub_f32_e32 v11, v30, v31
	v_add_f32_e32 v15, v26, v27
	v_cvt_pk_bf16_f32 v25, v11, v1
	v_cvt_pk_bf16_f32 v11, v15, v1
	global_load_dwordx2 v[26:27], v[20:21], off offset:32
	v_lshlrev_b32_e32 v29, 16, v12
	v_lshlrev_b32_e32 v28, 16, v16
	s_waitcnt vmcnt(0)
	v_pk_mul_f32 v[30:31], v[26:27], v[28:29] op_sel:[0,1] op_sel_hi:[1,0]
	v_pk_mul_f32 v[26:27], v[26:27], v[28:29]
	v_sub_f32_e32 v15, v30, v31
	v_add_f32_e32 v27, v26, v27
	v_cvt_pk_bf16_f32 v26, v15, v1
	v_cvt_pk_bf16_f32 v15, v27, v1
	global_load_dwordx2 v[28:29], v[20:21], off offset:40
	v_and_b32_e32 v31, 0xffff0000, v12
	v_and_b32_e32 v30, 0xffff0000, v16
	s_waitcnt vmcnt(0)
; __device__ __forceinline__ bf16_t cvt_bf16(float v) { return (bf16_t)(cvt_pk_bf16(v, 0.f) & 0xffffu); }
; template <int DQ, int TYPE>
; __device__ __forceinline__ void attn_item(PP p, int layer, int b, int h, int qt, char* lds, const int tid_, unsigned* next_ctr, volatile XLAS unsigned* slot) {
;     ...
;             for (int kk = 0; kk < 2; ++kk) {
;                 bf16x8 x1 = qf[8 + kk], x2 = qf[10 + kk], o1, o2;
; #pragma unroll
;                 for (int j = 0; j < 8; ++j) {
;                     const int f = 16 * kk + 8 * hh + j;
;                     const float cs = r64[2 * f], sn = r64[2 * f + 1];
;                     const float a = __uint_as_float(((unsigned)(unsigned short)x1[j]) << 16), bb = __uint_as_float(((unsigned)(unsigned short)x2[j]) << 16);
;                     o1[j] = (short)cvt_bf16(a * cs - bb * sn); o2[j] = (short)cvt_bf16(bb * cs + a * sn);
;                 }
;                 qf[8 + kk] = o1; qf[10 + kk] = o2;
;             }
	v_pk_mul_f32 v[32:33], v[28:29], v[30:31] op_sel:[0,1] op_sel_hi:[1,0]
	v_pk_mul_f32 v[28:29], v[28:29], v[30:31]
	v_sub_f32_e32 v12, v32, v33
	v_add_f32_e32 v16, v28, v29
	v_cvt_pk_bf16_f32 v27, v12, v1
	v_cvt_pk_bf16_f32 v12, v16, v1
	global_load_dwordx2 v[28:29], v[20:21], off offset:48
	v_lshlrev_b32_e32 v31, 16, v13
	v_lshlrev_b32_e32 v30, 16, v17
	s_waitcnt vmcnt(0)
	v_pk_mul_f32 v[32:33], v[28:29], v[30:31] op_sel:[0,1] op_sel_hi:[1,0]
	v_pk_mul_f32 v[28:29], v[28:29], v[30:31]
	v_sub_f32_e32 v16, v32, v33
	v_add_f32_e32 v29, v28, v29
	v_cvt_pk_bf16_f32 v28, v16, v1
	v_cvt_pk_bf16_f32 v16, v29, v1
	global_load_dwordx2 v[30:31], v[20:21], off offset:56
	v_and_b32_e32 v33, 0xffff0000, v13
	v_and_b32_e32 v32, 0xffff0000, v17
	s_waitcnt vmcnt(0)
	v_pk_mul_f32 v[34:35], v[30:31], v[32:33] op_sel:[0,1] op_sel_hi:[1,0]
	v_pk_mul_f32 v[30:31], v[30:31], v[32:33]
	v_sub_f32_e32 v13, v34, v35
	v_add_f32_e32 v17, v30, v31
	v_cvt_pk_bf16_f32 v30, v13, v1
	v_cvt_pk_bf16_f32 v17, v17, v1
	global_load_dwordx2 v[32:33], v[20:21], off offset:128
	v_lshlrev_b32_e32 v35, 16, v2
	v_lshlrev_b32_e32 v34, 16, v6
	s_waitcnt vmcnt(0)
	v_pk_mul_f32 v[36:37], v[32:33], v[34:35] op_sel:[0,1] op_sel_hi:[1,0]
	v_pk_mul_f32 v[32:33], v[32:33], v[34:35]
	v_sub_f32_e32 v13, v36, v37
	v_add_f32_e32 v31, v32, v33
	v_cvt_pk_bf16_f32 v29, v13, v1
	v_cvt_pk_bf16_f32 v13, v31, v1
	global_load_dwordx2 v[32:33], v[20:21], off offset:136
	v_and_b32_e32 v35, 0xffff0000, v2
	v_and_b32_e32 v34, 0xffff0000, v6
	s_waitcnt vmcnt(0)
	v_pk_mul_f32 v[36:37], v[32:33], v[34:35] op_sel:[0,1] op_sel_hi:[1,0]
	v_pk_mul_f32 v[32:33], v[32:33], v[34:35]
	v_sub_f32_e32 v2, v36, v37
	v_add_f32_e32 v6, v32, v33
	v_cvt_pk_bf16_f32 v31, v2, v1
	v_cvt_pk_bf16_f32 v2, v6, v1
	global_load_dwordx2 v[32:33], v[20:21], off offset:144
	v_lshlrev_b32_e32 v35, 16, v3
	v_lshlrev_b32_e32 v34, 16, v7
	s_waitcnt vmcnt(0)
	v_pk_mul_f32 v[36:37], v[32:33], v[34:35] op_sel:[0,1] op_sel_hi:[1,0]
	v_pk_mul_f32 v[32:33], v[32:33], v[34:35]
	v_sub_f32_e32 v6, v36, v37
	v_add_f32_e32 v33, v32, v33
	v_cvt_pk_bf16_f32 v32, v6, v1
	v_cvt_pk_bf16_f32 v6, v33, v1
	global_load_dwordx2 v[34:35], v[20:21], off offset:152
	v_and_b32_e32 v37, 0xffff0000, v3
	v_and_b32_e32 v36, 0xffff0000, v7
	s_waitcnt vmcnt(0)
	v_pk_mul_f32 v[38:39], v[34:35], v[36:37] op_sel:[0,1] op_sel_hi:[1,0]
	v_pk_mul_f32 v[34:35], v[34:35], v[36:37]
	v_sub_f32_e32 v3, v38, v39
	v_add_f32_e32 v7, v34, v35
	v_cvt_pk_bf16_f32 v33, v3, v1
	v_cvt_pk_bf16_f32 v3, v7, v1
	global_load_dwordx2 v[34:35], v[20:21], off offset:160
	v_lshlrev_b32_e32 v37, 16, v4
	v_lshlrev_b32_e32 v36, 16, v8
	s_waitcnt vmcnt(0)
	v_pk_mul_f32 v[38:39], v[34:35], v[36:37] op_sel:[0,1] op_sel_hi:[1,0]
	v_pk_mul_f32 v[34:35], v[34:35], v[36:37]
	v_sub_f32_e32 v7, v38, v39
	v_add_f32_e32 v35, v34, v35
	v_cvt_pk_bf16_f32 v34, v7, v1
	v_cvt_pk_bf16_f32 v7, v35, v1
	global_load_dwordx2 v[36:37], v[20:21], off offset:168
	v_and_b32_e32 v39, 0xffff0000, v4
	v_and_b32_e32 v38, 0xffff0000, v8
	s_waitcnt vmcnt(0)
	v_pk_mul_f32 v[40:41], v[36:37], v[38:39] op_sel:[0,1] op_sel_hi:[1,0]
	v_pk_mul_f32 v[36:37], v[36:37], v[38:39]
	v_sub_f32_e32 v4, v40, v41
	v_add_f32_e32 v8, v36, v37
	v_cvt_pk_bf16_f32 v35, v4, v1
	v_cvt_pk_bf16_f32 v4, v8, v1
	global_load_dwordx2 v[36:37], v[20:21], off offset:176
	v_lshlrev_b32_e32 v39, 16, v5
	v_lshlrev_b32_e32 v38, 16, v9
	s_waitcnt vmcnt(0)
	v_pk_mul_f32 v[40:41], v[36:37], v[38:39] op_sel:[0,1] op_sel_hi:[1,0]
	v_pk_mul_f32 v[36:37], v[36:37], v[38:39]
	v_sub_f32_e32 v8, v40, v41
	v_add_f32_e32 v37, v36, v37
	v_cvt_pk_bf16_f32 v36, v8, v1
	v_cvt_pk_bf16_f32 v8, v37, v1
	global_load_dwordx2 v[20:21], v[20:21], off offset:184
	v_mul_u32_u24_e32 v37, 15, v185
	v_lshlrev_b32_e32 v38, 2, v166
	v_mul_lo_u32 v39, v174, s8
	v_add3_u32 v37, v18, v37, v38
	v_lshlrev_b32_e32 v194, 1, v39
	v_and_b32_e32 v38, 0xffff, v114
	v_lshrrev_b32_e32 v39, 16, v114
	v_and_b32_e32 v40, 0xffff, v115
	v_lshrrev_b32_e32 v41, 16, v115
	v_lshl_or_b32 v48, v122, 16, v38
	v_and_or_b32 v49, v122, s91, v39
	v_and_b32_e32 v39, 0xffff0000, v5
	v_and_b32_e32 v38, 0xffff0000, v9
	s_cselect_b64 s[8:9], -1, 0
	v_lshl_or_b32 v50, v123, 16, v40
	v_and_or_b32 v51, v123, s91, v41
	s_and_b64 vcc, exec, s[8:9]
	v_add_u32_e32 v18, v18, v193
	v_add3_u32 v43, 16, v194, v0
	v_add_u32_e32 v37, 0x6400, v37
	s_waitcnt vmcnt(0)
	v_pk_mul_f32 v[40:41], v[20:21], v[38:39] op_sel:[0,1] op_sel_hi:[1,0]
	v_pk_mul_f32 v[20:21], v[20:21], v[38:39]
	v_sub_f32_e32 v5, v40, v41
	v_add_f32_e32 v20, v20, v21
	v_cvt_pk_bf16_f32 v9, v5, v1
	v_cvt_pk_bf16_f32 v5, v20, v1
	ds_write_b128 v42, v[86:89]
	ds_write_b128 v18, v[90:93]
	ds_write_b128 v43, v[118:121] offset:256
	ds_write_b32 v37, v48
	ds_write_b32 v37, v49 offset:2448
	ds_write_b32 v37, v50 offset:4896
	ds_write_b32 v37, v51 offset:7344
	ds_write_b32 v37, v44 offset:9792
	ds_write_b32 v37, v45 offset:12240
	ds_write_b32 v37, v46 offset:14688
	ds_write_b32 v37, v47 offset:17136
	s_waitcnt lgkmcnt(0)
	s_barrier
	s_mov_b32 s32, 0
	s_cbranch_vccnz .LBB0_661
	s_setprio 2
	s_mov_b32 s32, 1

; template <int DQ, int TYPE>
; __device__ __forceinline__ void attn_item(PP p, int layer, int b, int h, int qt, char* lds, const int tid_, unsigned* next_ctr, volatile XLAS unsigned* slot) {
;     ...
;     for (int j = j_lo; j <= j_hi; ++j) {
;         const int buf = (j - j_lo) & 1;
;         if (j < j_hi) A_GLOAD(A, j + 1);
.LBB0_662:
	v_mov_b32_e32 v205, v200
	s_cmp_le_u32 s51, s16
	s_cselect_b64 s[12:13], -1, 0
	s_cmp_gt_u32 s51, s16
	s_cbranch_scc1 .LBB0_664
	s_cmp_lg_u32 s32, 0
	s_cbranch_scc1 .LBB0_664

; template <int DQ, int TYPE>
; __device__ __forceinline__ void attn_item(PP p, int layer, int b, int h, int qt, char* lds, const int tid_, unsigned* next_ctr, volatile XLAS unsigned* slot) {
;     ...
;         if (j < j_hi) A_GLOAD(A, j + 1);
;     ...
;         if (j < j_hi) A_LSTORE(A, buf ^ 1);
;         __syncthreads();
.LBB0_672:
	s_add_i32 s51, s51, 1
	s_add_i32 s57, s57, 64
	s_waitcnt lgkmcnt(0)
	s_cmp_eq_u32 s32, 0
	s_cbranch_scc1 .Lmla_noearly
	s_cmp_eq_u32 s49, s51
	s_cbranch_scc1 .Lmla_noearly
	s_cmp_gt_u32 s51, s16
	s_cbranch_scc1 .Lmla_noearly
	global_load_dwordx4 v[86:89], v[232:233], off
	global_load_dwordx4 v[90:93], v[234:235], off
	global_load_dwordx4 v[118:121], v[238:239], off
	global_load_dwordx4 v[114:117], v[236:237], off offset:256
	global_load_dwordx4 v[122:125], v[236:237], off offset:2304
	v_lshl_add_u64 v[232:233], s[98:99], 0, v[232:233]
	v_lshl_add_u64 v[234:235], s[98:99], 0, v[234:235]
	v_lshl_add_u64 v[236:237], s[98:99], 0, v[236:237]
	v_add_co_u32_e32 v238, vcc, 0x2000, v238
	v_addc_co_u32_e32 v239, vcc, 0, v239, vcc
.Lmla_noearly:
	s_cmp_eq_u32 s49, s51
	s_barrier
	s_cbranch_scc0 .LBB0_662
	s_setprio 0
	v_mov_b32_e32 v74, 0
	v_cmp_eq_u32_e64 s[50:51], 0, v181
	s_and_saveexec_b64 s[12:13], s[50:51]
	s_cbranch_execz .LBB0_677
	s_mov_b64 s[16:17], exec
	v_mbcnt_lo_u32_b32 v0, s16, 0
	v_mbcnt_hi_u32_b32 v0, s17, v0
	v_cmp_eq_u32_e32 vcc, 0, v0
	s_and_saveexec_b64 s[14:15], vcc
	s_cbranch_execz .LBB0_676
	s_bcnt1_i32_b64 s16, s[16:17]
	s_lshl_b32 s17, s47, 2
	v_mov_b32_e32 v66, s17
	v_mov_b32_e32 v67, s16
	global_atomic_add v250, v66, v67, s[6:7] sc0
